# touch the whole residual tile (256 rows) in the second-to-last K iteration of out-proj/FF2
# baseline (speedup 1.0000x reference)
.LBB0_228:
	s_and_b32 s48, s48, 7
	s_or_b32 s73, s48, s4
	s_and_b64 s[48:49], s[46:47], exec
	s_cselect_b32 s48, s73, s29
	s_ashr_i32 s49, s48, 31
	s_lshl_b64 s[48:49], s[48:49], 21
	v_readlane_b32 s29, v236, 61
	s_add_u32 s48, s29, s48
	v_readlane_b32 s29, v236, 58
	v_mov_b32_e32 v125, 0
	s_addc_u32 s49, s29, s49
	s_andn2_b64 vcc, exec, s[42:43]
	v_mov_b32_e32 v124, v125
	v_mov_b32_e32 v123, v125
	v_mov_b32_e32 v122, v125
	v_mov_b32_e32 v129, v125
	v_mov_b32_e32 v128, v125
	v_mov_b32_e32 v127, v125
	v_mov_b32_e32 v126, v125
	v_mov_b32_e32 v113, v125
	v_mov_b32_e32 v112, v125
	v_mov_b32_e32 v111, v125
	v_mov_b32_e32 v110, v125
	v_mov_b32_e32 v109, v125
	v_mov_b32_e32 v108, v125
	v_mov_b32_e32 v107, v125
	v_mov_b32_e32 v106, v125
	v_mov_b32_e32 v97, v125
	v_mov_b32_e32 v96, v125
	v_mov_b32_e32 v95, v125
	v_mov_b32_e32 v94, v125
	v_mov_b32_e32 v93, v125
	v_mov_b32_e32 v92, v125
	v_mov_b32_e32 v91, v125
	v_mov_b32_e32 v90, v125
	v_mov_b32_e32 v81, v125
	v_mov_b32_e32 v80, v125
	v_mov_b32_e32 v79, v125
	v_mov_b32_e32 v78, v125
	v_mov_b32_e32 v77, v125
	v_mov_b32_e32 v76, v125
	v_mov_b32_e32 v75, v125
	v_mov_b32_e32 v74, v125
	v_mov_b32_e32 v121, v125
	v_mov_b32_e32 v120, v125
	v_mov_b32_e32 v119, v125
	v_mov_b32_e32 v118, v125
	v_mov_b32_e32 v117, v125
	v_mov_b32_e32 v116, v125
	v_mov_b32_e32 v115, v125
	v_mov_b32_e32 v114, v125
	v_mov_b32_e32 v105, v125
	v_mov_b32_e32 v104, v125
	v_mov_b32_e32 v103, v125
	v_mov_b32_e32 v102, v125
	v_mov_b32_e32 v101, v125
	v_mov_b32_e32 v100, v125
	v_mov_b32_e32 v99, v125
	v_mov_b32_e32 v98, v125
	v_mov_b32_e32 v89, v125
	v_mov_b32_e32 v88, v125
	v_mov_b32_e32 v87, v125
	v_mov_b32_e32 v86, v125
	v_mov_b32_e32 v85, v125
	v_mov_b32_e32 v84, v125
	v_mov_b32_e32 v83, v125
	v_mov_b32_e32 v82, v125
	v_mov_b32_e32 v73, v125
	v_mov_b32_e32 v72, v125
	v_mov_b32_e32 v71, v125
	v_mov_b32_e32 v70, v125
	v_mov_b32_e32 v69, v125
	v_mov_b32_e32 v68, v125
	v_mov_b32_e32 v67, v125
	v_mov_b32_e32 v66, v125
	v_mov_b32_e32 v65, v125
	v_mov_b32_e32 v64, v125
	v_mov_b32_e32 v63, v125
	v_mov_b32_e32 v62, v125
	v_mov_b32_e32 v61, v125
	v_mov_b32_e32 v60, v125
	v_mov_b32_e32 v59, v125
	v_mov_b32_e32 v58, v125
	v_mov_b32_e32 v49, v125
	v_mov_b32_e32 v48, v125
	v_mov_b32_e32 v47, v125
	v_mov_b32_e32 v46, v125
	v_mov_b32_e32 v45, v125
	v_mov_b32_e32 v44, v125
	v_mov_b32_e32 v43, v125
	v_mov_b32_e32 v42, v125
	v_mov_b32_e32 v33, v125
	v_mov_b32_e32 v32, v125
	v_mov_b32_e32 v31, v125
	v_mov_b32_e32 v30, v125
	v_mov_b32_e32 v29, v125
	v_mov_b32_e32 v28, v125
	v_mov_b32_e32 v27, v125
	v_mov_b32_e32 v26, v125
	v_mov_b32_e32 v17, v125
	v_mov_b32_e32 v16, v125
	v_mov_b32_e32 v15, v125
	v_mov_b32_e32 v14, v125
	v_mov_b32_e32 v13, v125
	v_mov_b32_e32 v12, v125
	v_mov_b32_e32 v11, v125
	v_mov_b32_e32 v10, v125
	v_mov_b32_e32 v57, v125
	v_mov_b32_e32 v56, v125
	v_mov_b32_e32 v55, v125
	v_mov_b32_e32 v54, v125
	v_mov_b32_e32 v53, v125
	v_mov_b32_e32 v52, v125
	v_mov_b32_e32 v51, v125
	v_mov_b32_e32 v50, v125
	v_mov_b32_e32 v41, v125
	v_mov_b32_e32 v40, v125
	v_mov_b32_e32 v39, v125
	v_mov_b32_e32 v38, v125
	v_mov_b32_e32 v37, v125
	v_mov_b32_e32 v36, v125
	v_mov_b32_e32 v35, v125
	v_mov_b32_e32 v34, v125
	v_mov_b32_e32 v25, v125
	v_mov_b32_e32 v24, v125
	v_mov_b32_e32 v23, v125
	v_mov_b32_e32 v22, v125
	v_mov_b32_e32 v21, v125
	v_mov_b32_e32 v20, v125
	v_mov_b32_e32 v19, v125
	v_mov_b32_e32 v18, v125
	v_mov_b32_e32 v9, v125
	v_mov_b32_e32 v8, v125
	v_mov_b32_e32 v7, v125
	v_mov_b32_e32 v6, v125
	v_mov_b32_e32 v5, v125
	v_mov_b32_e32 v4, v125
	s_waitcnt lgkmcnt(0)
	v_mov_b32_e32 v3, v125
	v_mov_b32_e32 v2, v125
	s_cbranch_vccnz .LBB0_232
	s_and_b64 s[50:51], s[46:47], exec
	s_cselect_b32 s29, s49, s57
	s_cselect_b32 s50, s48, s56
	s_add_u32 s56, s56, 0x80
	s_addc_u32 s57, s57, 0
	s_add_u32 s51, s58, 0x100
	v_mov_b32_e32 v2, 0
	s_addc_u32 s55, s59, 0
	s_mov_b32 s58, 0
	v_mov_b32_e32 v3, v2
	v_mov_b32_e32 v4, v2
	v_mov_b32_e32 v5, v2
	v_mov_b32_e32 v6, v2
	v_mov_b32_e32 v7, v2
	v_mov_b32_e32 v8, v2
	v_mov_b32_e32 v9, v2
	v_mov_b32_e32 v18, v2
	v_mov_b32_e32 v19, v2
	v_mov_b32_e32 v20, v2
	v_mov_b32_e32 v21, v2
	v_mov_b32_e32 v22, v2
	v_mov_b32_e32 v23, v2
	v_mov_b32_e32 v24, v2
	v_mov_b32_e32 v25, v2
	v_mov_b32_e32 v34, v2
	v_mov_b32_e32 v35, v2
	v_mov_b32_e32 v36, v2
	v_mov_b32_e32 v37, v2
	v_mov_b32_e32 v38, v2
	v_mov_b32_e32 v39, v2
	v_mov_b32_e32 v40, v2
	v_mov_b32_e32 v41, v2
	v_mov_b32_e32 v50, v2
	v_mov_b32_e32 v51, v2
	v_mov_b32_e32 v52, v2
	v_mov_b32_e32 v53, v2
	v_mov_b32_e32 v54, v2
	v_mov_b32_e32 v55, v2
	v_mov_b32_e32 v56, v2
	v_mov_b32_e32 v57, v2
	v_mov_b32_e32 v10, v2
	v_mov_b32_e32 v11, v2
	v_mov_b32_e32 v12, v2
	v_mov_b32_e32 v13, v2
	v_mov_b32_e32 v14, v2
	v_mov_b32_e32 v15, v2
	v_mov_b32_e32 v16, v2
	v_mov_b32_e32 v17, v2
	v_mov_b32_e32 v26, v2
	v_mov_b32_e32 v27, v2
	v_mov_b32_e32 v28, v2
	v_mov_b32_e32 v29, v2
	v_mov_b32_e32 v30, v2
	v_mov_b32_e32 v31, v2
	v_mov_b32_e32 v32, v2
	v_mov_b32_e32 v33, v2
	v_mov_b32_e32 v42, v2
	v_mov_b32_e32 v43, v2
	v_mov_b32_e32 v44, v2
	v_mov_b32_e32 v45, v2
	v_mov_b32_e32 v46, v2
	v_mov_b32_e32 v47, v2
	v_mov_b32_e32 v48, v2
	v_mov_b32_e32 v49, v2
	v_mov_b32_e32 v58, v2
	v_mov_b32_e32 v59, v2
	v_mov_b32_e32 v60, v2
	v_mov_b32_e32 v61, v2
	v_mov_b32_e32 v62, v2
	v_mov_b32_e32 v63, v2
	v_mov_b32_e32 v64, v2
	v_mov_b32_e32 v65, v2
	v_mov_b32_e32 v66, v2
	v_mov_b32_e32 v67, v2
	v_mov_b32_e32 v68, v2
	v_mov_b32_e32 v69, v2
	v_mov_b32_e32 v70, v2
	v_mov_b32_e32 v71, v2
	v_mov_b32_e32 v72, v2
	v_mov_b32_e32 v73, v2
	v_mov_b32_e32 v82, v2
	v_mov_b32_e32 v83, v2
	v_mov_b32_e32 v84, v2
	v_mov_b32_e32 v85, v2
	v_mov_b32_e32 v86, v2
	v_mov_b32_e32 v87, v2
	v_mov_b32_e32 v88, v2
	v_mov_b32_e32 v89, v2
	v_mov_b32_e32 v98, v2
	v_mov_b32_e32 v99, v2
	v_mov_b32_e32 v100, v2
	v_mov_b32_e32 v101, v2
	v_mov_b32_e32 v102, v2
	v_mov_b32_e32 v103, v2
	v_mov_b32_e32 v104, v2
	v_mov_b32_e32 v105, v2
	v_mov_b32_e32 v114, v2
	v_mov_b32_e32 v115, v2
	v_mov_b32_e32 v116, v2
	v_mov_b32_e32 v117, v2
	v_mov_b32_e32 v118, v2
	v_mov_b32_e32 v119, v2
	v_mov_b32_e32 v120, v2
	v_mov_b32_e32 v121, v2
	v_mov_b32_e32 v74, v2
	v_mov_b32_e32 v75, v2
	v_mov_b32_e32 v76, v2
	v_mov_b32_e32 v77, v2
	v_mov_b32_e32 v78, v2
	v_mov_b32_e32 v79, v2
	v_mov_b32_e32 v80, v2
	v_mov_b32_e32 v81, v2
	v_mov_b32_e32 v90, v2
	v_mov_b32_e32 v91, v2
	v_mov_b32_e32 v92, v2
	v_mov_b32_e32 v93, v2
	v_mov_b32_e32 v94, v2
	v_mov_b32_e32 v95, v2
	v_mov_b32_e32 v96, v2
	v_mov_b32_e32 v97, v2
	v_mov_b32_e32 v106, v2
	v_mov_b32_e32 v107, v2
	v_mov_b32_e32 v108, v2
	v_mov_b32_e32 v109, v2
	v_mov_b32_e32 v110, v2
	v_mov_b32_e32 v111, v2
	v_mov_b32_e32 v112, v2
	v_mov_b32_e32 v113, v2
	v_mov_b32_e32 v126, v2
	v_mov_b32_e32 v127, v2
	v_mov_b32_e32 v128, v2
	v_mov_b32_e32 v129, v2
	v_mov_b32_e32 v122, v2
	v_mov_b32_e32 v123, v2
	v_mov_b32_e32 v124, v2
	v_mov_b32_e32 v125, v2
	v_readlane_b32 s98, v235, 13
	v_readlane_b32 s99, v235, 14
	s_and_b32 s100, s54, 63
	s_and_b32 s101, s28, 3
	s_lshl_b32 s100, s100, 20
	s_lshl_b32 s101, s101, 10
	s_add_u32 s100, s100, s101
	s_add_u32 s98, s98, s100
	s_addc_u32 s99, s99, 0
	v_lshrrev_b32_e32 v240, 6, v190
	v_and_b32_e32 v241, 63, v190
	v_lshl_or_b32 v240, v240, 7, v241
	v_lshrrev_b32_e32 v241, 3, v240
	v_and_b32_e32 v240, 7, v240
	v_lshlrev_b32_e32 v241, 12, v241
	v_lshl_or_b32 v240, v240, 7, v241
	v_mov_b32_e32 v241, 0
	v_lshl_add_u64 v[238:239], s[98:99], 0, v[240:241]
	v_add_u32_e32 v240, 0x8000, v240
	v_lshl_add_u64 v[242:243], s[98:99], 0, v[240:241]
	v_add_u32_e32 v240, 0x78000, v240
	v_lshl_add_u64 v[246:247], s[98:99], 0, v[240:241]
	v_add_u32_e32 v240, 0x8000, v240
	v_lshl_add_u64 v[248:249], s[98:99], 0, v[240:241]
	s_mov_b32 s98, 0
.LBB0_230:
	s_add_i32 s74, s58, 2
	s_add_u32 s75, s56, 0x80
	s_addc_u32 s59, s57, 0
	s_add_i32 s78, 0, 0x10000
	s_cmp_eq_u32 s66, s58
	s_cselect_b32 s59, s29, s59
	s_cselect_b32 s58, s50, s75
	s_cselect_b32 s81, s45, s55
	s_cselect_b32 s80, s44, s51
	s_cmp_eq_u32 s74, s66
	s_cselect_b32 s98, 1, 0
	s_add_i32 s75, 0, 0x14000
	v_add_u32_e32 v156, s78, v146
	v_add_u32_e32 v172, s75, v146
	ds_read_b128 v[140:143], v156
	ds_read_b128 v[148:151], v156 offset:1024
	ds_read_b128 v[152:155], v156 offset:2048
	ds_read_b128 v[156:159], v156 offset:3072
	ds_read_b128 v[160:163], v172
	ds_read_b128 v[164:167], v172 offset:1024
	ds_read_b128 v[168:171], v172 offset:2048
	ds_read_b128 v[172:175], v172 offset:3072
	v_lshl_add_u64 v[188:189], s[56:57], 0, v[134:135]
	s_mov_b32 m0, s64
	ds_read_b128 v[176:179], v147
	ds_read_b128 v[180:183], v147 offset:1024
	ds_read_b128 v[184:187], v147 offset:2048
	ds_read_b128 v[200:203], v147 offset:3072
	ds_read_b128 v[204:207], v147 offset:4096
	ds_read_b128 v[208:211], v147 offset:5120
	ds_read_b128 v[212:215], v147 offset:6144
	ds_read_b128 v[216:219], v147 offset:7168
	global_load_lds_dwordx4 v[188:189], off
	v_lshl_add_u64 v[188:189], s[56:57], 0, v[132:133]
	s_mov_b32 m0, s65
	s_nop 0
	global_load_lds_dwordx4 v[188:189], off
	v_lshl_add_u64 v[188:189], s[56:57], 0, v[136:137]
	s_add_i32 m0, s27, 0xc000
	s_nop 0
	global_load_lds_dwordx4 v[188:189], off
	v_lshl_add_u64 v[188:189], s[56:57], 0, v[138:139]
	s_add_i32 m0, s27, 0xe000
	s_nop 0
	global_load_lds_dwordx4 v[188:189], off
	s_waitcnt vmcnt(8)
	s_waitcnt lgkmcnt(0)
	s_barrier
	s_setprio 1
	s_waitcnt lgkmcnt(0)
	v_mfma_f32_16x16x32_bf16 v[122:125], v[140:143], v[176:179], v[122:125]
	v_mfma_f32_16x16x32_bf16 v[126:129], v[152:155], v[176:179], v[126:129]
	v_mfma_f32_16x16x32_bf16 v[110:113], v[140:143], v[184:187], v[110:113]
	v_mfma_f32_16x16x32_bf16 v[106:109], v[152:155], v[184:187], v[106:109]
	v_mfma_f32_16x16x32_bf16 v[94:97], v[140:143], v[204:207], v[94:97]
	v_mfma_f32_16x16x32_bf16 v[90:93], v[152:155], v[204:207], v[90:93]
	v_mfma_f32_16x16x32_bf16 v[78:81], v[140:143], v[212:215], v[78:81]
	v_mfma_f32_16x16x32_bf16 v[74:77], v[152:155], v[212:215], v[74:77]
	v_mfma_f32_16x16x32_bf16 v[122:125], v[148:151], v[180:183], v[122:125]
	v_mfma_f32_16x16x32_bf16 v[126:129], v[156:159], v[180:183], v[126:129]
	v_mfma_f32_16x16x32_bf16 v[110:113], v[148:151], v[200:203], v[110:113]
	v_mfma_f32_16x16x32_bf16 v[106:109], v[156:159], v[200:203], v[106:109]
	v_mfma_f32_16x16x32_bf16 v[94:97], v[148:151], v[208:211], v[94:97]
	v_mfma_f32_16x16x32_bf16 v[90:93], v[156:159], v[208:211], v[90:93]
	v_mfma_f32_16x16x32_bf16 v[78:81], v[148:151], v[216:219], v[78:81]
	v_mfma_f32_16x16x32_bf16 v[74:77], v[156:159], v[216:219], v[74:77]
	s_setprio 0
	s_setprio 1
	v_mfma_f32_16x16x32_bf16 v[118:121], v[160:163], v[176:179], v[118:121]
	v_mfma_f32_16x16x32_bf16 v[114:117], v[168:171], v[176:179], v[114:117]
	v_mfma_f32_16x16x32_bf16 v[102:105], v[160:163], v[184:187], v[102:105]
	v_mfma_f32_16x16x32_bf16 v[98:101], v[168:171], v[184:187], v[98:101]
	v_mfma_f32_16x16x32_bf16 v[86:89], v[160:163], v[204:207], v[86:89]
	v_mfma_f32_16x16x32_bf16 v[82:85], v[168:171], v[204:207], v[82:85]
	v_mfma_f32_16x16x32_bf16 v[70:73], v[160:163], v[212:215], v[70:73]
	v_mfma_f32_16x16x32_bf16 v[66:69], v[168:171], v[212:215], v[66:69]
	v_mfma_f32_16x16x32_bf16 v[118:121], v[164:167], v[180:183], v[118:121]
	v_mfma_f32_16x16x32_bf16 v[114:117], v[172:175], v[180:183], v[114:117]
	v_mfma_f32_16x16x32_bf16 v[102:105], v[164:167], v[200:203], v[102:105]
	v_mfma_f32_16x16x32_bf16 v[98:101], v[172:175], v[200:203], v[98:101]
	v_mfma_f32_16x16x32_bf16 v[86:89], v[164:167], v[208:211], v[86:89]
	v_mfma_f32_16x16x32_bf16 v[82:85], v[172:175], v[208:211], v[82:85]
	v_mfma_f32_16x16x32_bf16 v[70:73], v[164:167], v[216:219], v[70:73]
	v_mfma_f32_16x16x32_bf16 v[66:69], v[172:175], v[216:219], v[66:69]
	s_setprio 0
	s_barrier
	s_add_i32 s78, s78, s5
	v_lshl_add_u64 v[188:189], s[80:81], 0, v[0:1]
	s_mov_b32 m0, s78
	ds_read_b128 v[176:179], v147 offset:16384
	ds_read_b128 v[180:183], v147 offset:17408
	ds_read_b128 v[184:187], v147 offset:18432
	ds_read_b128 v[200:203], v147 offset:19456
	ds_read_b128 v[204:207], v147 offset:20480
	ds_read_b128 v[208:211], v147 offset:21504
	ds_read_b128 v[212:215], v147 offset:22528
	ds_read_b128 v[216:219], v147 offset:23552
	global_load_lds_dwordx4 v[188:189], off
	s_add_i32 m0, s78, 0x2000
	v_lshl_add_u64 v[220:221], s[80:81], 0, v[130:131]
	s_add_u32 s80, s80, s6
	s_addc_u32 s81, s81, s7
	s_add_i32 s75, s75, s5
	global_load_lds_dwordx4 v[220:221], off
	v_lshl_add_u64 v[222:223], s[80:81], 0, v[0:1]
	s_mov_b32 m0, s75
	v_lshl_add_u64 v[224:225], s[80:81], 0, v[130:131]
	global_load_lds_dwordx4 v[222:223], off
	s_add_i32 m0, s75, 0x2000
	v_lshl_add_u64 v[226:227], s[58:59], 0, v[134:135]
	global_load_lds_dwordx4 v[224:225], off
	v_lshl_add_u64 v[228:229], s[58:59], 0, v[132:133]
	s_waitcnt vmcnt(6)
	s_waitcnt lgkmcnt(0)
	s_barrier
	s_setprio 1
	s_waitcnt lgkmcnt(0)
	v_mfma_f32_16x16x32_bf16 v[62:65], v[140:143], v[176:179], v[62:65]
	v_mfma_f32_16x16x32_bf16 v[58:61], v[152:155], v[176:179], v[58:61]
	v_mfma_f32_16x16x32_bf16 v[46:49], v[140:143], v[184:187], v[46:49]
	v_mfma_f32_16x16x32_bf16 v[42:45], v[152:155], v[184:187], v[42:45]
	v_mfma_f32_16x16x32_bf16 v[30:33], v[140:143], v[204:207], v[30:33]
	v_mfma_f32_16x16x32_bf16 v[26:29], v[152:155], v[204:207], v[26:29]
	v_mfma_f32_16x16x32_bf16 v[14:17], v[140:143], v[212:215], v[14:17]
	v_mfma_f32_16x16x32_bf16 v[10:13], v[152:155], v[212:215], v[10:13]
	v_mfma_f32_16x16x32_bf16 v[62:65], v[148:151], v[180:183], v[62:65]
	v_mfma_f32_16x16x32_bf16 v[58:61], v[156:159], v[180:183], v[58:61]
	v_mfma_f32_16x16x32_bf16 v[46:49], v[148:151], v[200:203], v[46:49]
	v_mfma_f32_16x16x32_bf16 v[42:45], v[156:159], v[200:203], v[42:45]
	v_mfma_f32_16x16x32_bf16 v[30:33], v[148:151], v[208:211], v[30:33]
	v_mfma_f32_16x16x32_bf16 v[26:29], v[156:159], v[208:211], v[26:29]
	v_mfma_f32_16x16x32_bf16 v[14:17], v[148:151], v[216:219], v[14:17]
	v_mfma_f32_16x16x32_bf16 v[10:13], v[156:159], v[216:219], v[10:13]
	s_setprio 0
	s_setprio 1
	v_mfma_f32_16x16x32_bf16 v[54:57], v[160:163], v[176:179], v[54:57]
	v_mfma_f32_16x16x32_bf16 v[50:53], v[168:171], v[176:179], v[50:53]
	v_mfma_f32_16x16x32_bf16 v[38:41], v[160:163], v[184:187], v[38:41]
	v_mfma_f32_16x16x32_bf16 v[34:37], v[168:171], v[184:187], v[34:37]
	v_mfma_f32_16x16x32_bf16 v[22:25], v[160:163], v[204:207], v[22:25]
	v_mfma_f32_16x16x32_bf16 v[18:21], v[168:171], v[204:207], v[18:21]
	v_mfma_f32_16x16x32_bf16 v[6:9], v[160:163], v[212:215], v[6:9]
	v_mfma_f32_16x16x32_bf16 v[2:5], v[168:171], v[212:215], v[2:5]
	v_mfma_f32_16x16x32_bf16 v[54:57], v[164:167], v[180:183], v[54:57]
	v_mfma_f32_16x16x32_bf16 v[50:53], v[172:175], v[180:183], v[50:53]
	v_mfma_f32_16x16x32_bf16 v[38:41], v[164:167], v[200:203], v[38:41]
	v_mfma_f32_16x16x32_bf16 v[34:37], v[172:175], v[200:203], v[34:37]
	v_mfma_f32_16x16x32_bf16 v[22:25], v[164:167], v[208:211], v[22:25]
	v_mfma_f32_16x16x32_bf16 v[18:21], v[172:175], v[208:211], v[18:21]
	v_mfma_f32_16x16x32_bf16 v[6:9], v[164:167], v[216:219], v[6:9]
	v_mfma_f32_16x16x32_bf16 v[2:5], v[172:175], v[216:219], v[2:5]
	s_setprio 0
	s_barrier
	s_add_i32 s75, 0, 0x18000
	s_add_i32 s78, 0, 0x1c000
	v_add_u32_e32 v156, s75, v146
	v_add_u32_e32 v172, s78, v146
	ds_read_b128 v[140:143], v156
	ds_read_b128 v[148:151], v156 offset:1024
	ds_read_b128 v[152:155], v156 offset:2048
	ds_read_b128 v[156:159], v156 offset:3072
	ds_read_b128 v[160:163], v172
	ds_read_b128 v[164:167], v172 offset:1024
	ds_read_b128 v[168:171], v172 offset:2048
	ds_read_b128 v[172:175], v172 offset:3072
	s_add_u32 s58, s58, s2
	s_addc_u32 s59, s59, s3
	s_mov_b32 m0, s27
	v_lshl_add_u64 v[230:231], s[58:59], 0, v[134:135]
	ds_read_b128 v[176:179], v147 offset:32768
	ds_read_b128 v[180:183], v147 offset:33792
	ds_read_b128 v[184:187], v147 offset:34816
	ds_read_b128 v[200:203], v147 offset:35840
	ds_read_b128 v[204:207], v147 offset:36864
	ds_read_b128 v[208:211], v147 offset:37888
	ds_read_b128 v[212:215], v147 offset:38912
	ds_read_b128 v[216:219], v147 offset:39936
	global_load_lds_dwordx4 v[226:227], off
	s_mov_b32 m0, s30
	s_nop 0
	global_load_lds_dwordx4 v[228:229], off
	s_mov_b32 m0, s31
	s_nop 0
	global_load_lds_dwordx4 v[230:231], off
	v_lshl_add_u64 v[230:231], s[58:59], 0, v[132:133]
	s_mov_b32 m0, s53
	s_nop 0
	global_load_lds_dwordx4 v[230:231], off
	s_waitcnt vmcnt(8)
	s_waitcnt lgkmcnt(0)
	s_barrier
	s_setprio 1
	s_waitcnt lgkmcnt(0)
	v_mfma_f32_16x16x32_bf16 v[122:125], v[140:143], v[176:179], v[122:125]
	v_mfma_f32_16x16x32_bf16 v[126:129], v[152:155], v[176:179], v[126:129]
	v_mfma_f32_16x16x32_bf16 v[110:113], v[140:143], v[184:187], v[110:113]
	v_mfma_f32_16x16x32_bf16 v[106:109], v[152:155], v[184:187], v[106:109]
	v_mfma_f32_16x16x32_bf16 v[94:97], v[140:143], v[204:207], v[94:97]
	v_mfma_f32_16x16x32_bf16 v[90:93], v[152:155], v[204:207], v[90:93]
	v_mfma_f32_16x16x32_bf16 v[78:81], v[140:143], v[212:215], v[78:81]
	v_mfma_f32_16x16x32_bf16 v[74:77], v[152:155], v[212:215], v[74:77]
	v_mfma_f32_16x16x32_bf16 v[122:125], v[148:151], v[180:183], v[122:125]
	v_mfma_f32_16x16x32_bf16 v[126:129], v[156:159], v[180:183], v[126:129]
	v_mfma_f32_16x16x32_bf16 v[110:113], v[148:151], v[200:203], v[110:113]
	v_mfma_f32_16x16x32_bf16 v[106:109], v[156:159], v[200:203], v[106:109]
	v_mfma_f32_16x16x32_bf16 v[94:97], v[148:151], v[208:211], v[94:97]
	v_mfma_f32_16x16x32_bf16 v[90:93], v[156:159], v[208:211], v[90:93]
	v_mfma_f32_16x16x32_bf16 v[78:81], v[148:151], v[216:219], v[78:81]
	v_mfma_f32_16x16x32_bf16 v[74:77], v[156:159], v[216:219], v[74:77]
	s_setprio 0
	s_setprio 1
	v_mfma_f32_16x16x32_bf16 v[118:121], v[160:163], v[176:179], v[118:121]
	v_mfma_f32_16x16x32_bf16 v[114:117], v[168:171], v[176:179], v[114:117]
	v_mfma_f32_16x16x32_bf16 v[102:105], v[160:163], v[184:187], v[102:105]
	v_mfma_f32_16x16x32_bf16 v[98:101], v[168:171], v[184:187], v[98:101]
	v_mfma_f32_16x16x32_bf16 v[86:89], v[160:163], v[204:207], v[86:89]
	v_mfma_f32_16x16x32_bf16 v[82:85], v[168:171], v[204:207], v[82:85]
	v_mfma_f32_16x16x32_bf16 v[70:73], v[160:163], v[212:215], v[70:73]
	v_mfma_f32_16x16x32_bf16 v[66:69], v[168:171], v[212:215], v[66:69]
	v_mfma_f32_16x16x32_bf16 v[118:121], v[164:167], v[180:183], v[118:121]
	v_mfma_f32_16x16x32_bf16 v[114:117], v[172:175], v[180:183], v[114:117]
	v_mfma_f32_16x16x32_bf16 v[102:105], v[164:167], v[200:203], v[102:105]
	v_mfma_f32_16x16x32_bf16 v[98:101], v[172:175], v[200:203], v[98:101]
	v_mfma_f32_16x16x32_bf16 v[86:89], v[164:167], v[208:211], v[86:89]
	v_mfma_f32_16x16x32_bf16 v[82:85], v[172:175], v[208:211], v[82:85]
	v_mfma_f32_16x16x32_bf16 v[70:73], v[164:167], v[216:219], v[70:73]
	v_mfma_f32_16x16x32_bf16 v[66:69], v[172:175], v[216:219], v[66:69]
	s_setprio 0
	s_barrier
	s_add_i32 s58, s75, s5
	v_lshl_add_u64 v[188:189], v[188:189], 0, s[24:25]
	s_mov_b32 m0, s58
	ds_read_b128 v[176:179], v147 offset:49152
	ds_read_b128 v[180:183], v147 offset:50176
	ds_read_b128 v[184:187], v147 offset:51200
	ds_read_b128 v[200:203], v147 offset:52224
	ds_read_b128 v[204:207], v147 offset:53248
	ds_read_b128 v[208:211], v147 offset:54272
	ds_read_b128 v[212:215], v147 offset:55296
	ds_read_b128 v[216:219], v147 offset:56320
	global_load_lds_dwordx4 v[188:189], off
	v_lshl_add_u64 v[188:189], v[220:221], 0, s[24:25]
	s_add_i32 m0, s58, 0x2000
	s_add_i32 s58, s78, s5
	global_load_lds_dwordx4 v[188:189], off
	v_lshl_add_u64 v[188:189], v[222:223], 0, s[24:25]
	s_mov_b32 m0, s58
	s_nop 0
	global_load_lds_dwordx4 v[188:189], off
	v_lshl_add_u64 v[188:189], v[224:225], 0, s[24:25]
	s_add_i32 m0, s58, 0x2000
	s_nop 0
	global_load_lds_dwordx4 v[188:189], off
	s_cmp_lg_u32 s98, 0
	s_cbranch_scc0 .Ltouch_skip_er
	global_load_dword v244, v[238:239], off
	global_load_dword v245, v[242:243], off
	global_load_dword v244, v[246:247], off
	global_load_dword v245, v[248:249], off

	.amdhsa_kernel _Z10fwd_kernel4Args
		.amdhsa_group_segment_fixed_size 0
		.amdhsa_private_segment_fixed_size 0
		.amdhsa_kernarg_size 400
		.amdhsa_user_sgpr_count 2
		.amdhsa_user_sgpr_dispatch_ptr 0
		.amdhsa_user_sgpr_queue_ptr 0
		.amdhsa_user_sgpr_kernarg_segment_ptr 1
		.amdhsa_user_sgpr_dispatch_id 0
		.amdhsa_user_sgpr_kernarg_preload_length 0
		.amdhsa_user_sgpr_kernarg_preload_offset 0
		.amdhsa_user_sgpr_private_segment_size 0
		.amdhsa_uses_dynamic_stack 0
		.amdhsa_enable_private_segment 0
		.amdhsa_system_sgpr_workgroup_id_x 1
		.amdhsa_system_sgpr_workgroup_id_y 0
		.amdhsa_system_sgpr_workgroup_id_z 0
		.amdhsa_system_sgpr_workgroup_info 0
		.amdhsa_system_vgpr_workitem_id 2
		.amdhsa_next_free_vgpr 250
		.amdhsa_next_free_sgpr 102
		.amdhsa_accum_offset 252
		.amdhsa_reserve_vcc 1
		.amdhsa_float_round_mode_32 0
		.amdhsa_float_round_mode_16_64 0
		.amdhsa_float_denorm_mode_32 3
		.amdhsa_float_denorm_mode_16_64 3
		.amdhsa_dx10_clamp 1
		.amdhsa_ieee_mode 1
		.amdhsa_fp16_overflow 0
		.amdhsa_tg_split 0
		.amdhsa_exception_fp_ieee_invalid_op 0
		.amdhsa_exception_fp_denorm_src 0
		.amdhsa_exception_fp_ieee_div_zero 0
		.amdhsa_exception_fp_ieee_overflow 0
		.amdhsa_exception_fp_ieee_underflow 0
		.amdhsa_exception_fp_ieee_inexact 0
		.amdhsa_exception_int_div_zero 0
	.end_amdhsa_kernel

amdhsa.kernels:
  - .agpr_count:     0
    .args:
      - .offset:         0
        .size:           144
        .value_kind:     by_value
      - .offset:         144
        .size:           4
        .value_kind:     hidden_block_count_x
      - .offset:         148
        .size:           4
        .value_kind:     hidden_block_count_y
      - .offset:         152
        .size:           4
        .value_kind:     hidden_block_count_z
      - .offset:         156
        .size:           2
        .value_kind:     hidden_group_size_x
      - .offset:         158
        .size:           2
        .value_kind:     hidden_group_size_y
      - .offset:         160
        .size:           2
        .value_kind:     hidden_group_size_z
      - .offset:         162
        .size:           2
        .value_kind:     hidden_remainder_x
      - .offset:         164
        .size:           2
        .value_kind:     hidden_remainder_y
      - .offset:         166
        .size:           2
        .value_kind:     hidden_remainder_z
      - .offset:         184
        .size:           8
        .value_kind:     hidden_global_offset_x
      - .offset:         192
        .size:           8
        .value_kind:     hidden_global_offset_y
      - .offset:         200
        .size:           8
        .value_kind:     hidden_global_offset_z
      - .offset:         208
        .size:           2
        .value_kind:     hidden_grid_dims
      - .offset:         232
        .size:           8
        .value_kind:     hidden_multigrid_sync_arg
      - .offset:         264
        .size:           4
        .value_kind:     hidden_dynamic_lds_size
    .group_segment_fixed_size: 0
    .kernarg_segment_align: 8
    .kernarg_segment_size: 400
    .language:       OpenCL C
    .language_version:
      - 2
      - 0
    .max_flat_workgroup_size: 512
    .name:           _Z10fwd_kernel4Args
    .private_segment_fixed_size: 0
    .sgpr_count:     108
    .sgpr_spill_count: 216
    .symbol:         _Z10fwd_kernel4Args.kd
    .uniform_work_group_size: 1
    .uses_dynamic_stack: false
    .vgpr_count:     250
    .vgpr_spill_count: 0
    .wavefront_size: 64
